# attention row sums moved under the PV MFMAs of the second key half; conv LDS fill loads issued together instead of one round trip each
# speedup vs baseline: 1.0174x; 1.0002x over previous
.LBB0_452:
	s_lshl_b32 s20, s71, 7
	s_and_b32 s16, s20, 0x780
	s_sub_i32 s21, 29, s16
	s_mov_b64 s[16:17], 0
	v_mov_b32_e32 v112, v204
	v_mov_b32_e32 v113, v189
	v_mov_b32_e32 v114, v203
	s_waitcnt vmcnt(0)
	s_barrier
	v_add_u32_e32 v122, s38, v113
	v_ashrrev_i32_e32 v123, 31, v122
	v_lshlrev_b64 v[120:121], 11, v[122:123]
	v_lshl_add_u64 v[120:121], v[110:111], 0, v[120:121]
	s_mov_b32 s18, 0x2000
	s_mov_b32 s19, 0
	v_mov_b64_e32 v[0:1], 0
	v_mov_b64_e32 v[2:3], 0
	v_mov_b64_e32 v[4:5], 0
	v_mov_b64_e32 v[6:7], 0
	v_mov_b64_e32 v[8:9], 0
	v_mov_b64_e32 v[10:11], 0
	v_mov_b64_e32 v[12:13], 0
	v_mov_b64_e32 v[14:15], 0
	v_mov_b64_e32 v[16:17], 0
	v_mov_b64_e32 v[18:19], 0
	v_mov_b64_e32 v[20:21], 0
	v_mov_b64_e32 v[22:23], 0
	v_mov_b64_e32 v[24:25], 0
	v_mov_b64_e32 v[26:27], 0
	v_mov_b64_e32 v[28:29], 0
	v_mov_b64_e32 v[30:31], 0
	v_mov_b64_e32 v[156:157], 0
	v_mov_b64_e32 v[158:159], 0
	v_mov_b64_e32 v[160:161], 0
	v_mov_b64_e32 v[162:163], 0
	v_mov_b64_e32 v[164:165], 0
	v_mov_b64_e32 v[166:167], 0
	v_mov_b64_e32 v[168:169], 0
	v_mov_b64_e32 v[170:171], 0
	v_mov_b64_e32 v[172:173], 0
	v_mov_b64_e32 v[174:175], 0
	v_mov_b64_e32 v[176:177], 0
	v_mov_b64_e32 v[178:179], 0
	v_mov_b64_e32 v[180:181], 0
	v_mov_b64_e32 v[182:183], 0
	v_mov_b64_e32 v[116:117], 0
	v_mov_b64_e32 v[118:119], 0
	v_cmp_lt_i32_e32 vcc, s21, v113
	s_and_saveexec_b64 s[16:17], vcc
	global_load_dwordx4 v[0:3], v[120:121], off
	s_mov_b64 exec, s[16:17]
	v_add_u32_e32 v113, 4, v113
	v_lshl_add_u64 v[120:121], v[120:121], 0, s[18:19]
	v_cmp_lt_i32_e32 vcc, s21, v113
	s_and_saveexec_b64 s[16:17], vcc
	global_load_dwordx4 v[4:7], v[120:121], off
	s_mov_b64 exec, s[16:17]
	v_add_u32_e32 v113, 4, v113
	v_lshl_add_u64 v[120:121], v[120:121], 0, s[18:19]
	v_cmp_lt_i32_e32 vcc, s21, v113
	s_and_saveexec_b64 s[16:17], vcc
	global_load_dwordx4 v[8:11], v[120:121], off
	s_mov_b64 exec, s[16:17]
	v_add_u32_e32 v113, 4, v113
	v_lshl_add_u64 v[120:121], v[120:121], 0, s[18:19]
	v_cmp_lt_i32_e32 vcc, s21, v113
	s_and_saveexec_b64 s[16:17], vcc
	global_load_dwordx4 v[12:15], v[120:121], off
	s_mov_b64 exec, s[16:17]
	v_add_u32_e32 v113, 4, v113
	v_lshl_add_u64 v[120:121], v[120:121], 0, s[18:19]
	v_cmp_lt_i32_e32 vcc, s21, v113
	s_and_saveexec_b64 s[16:17], vcc
	global_load_dwordx4 v[16:19], v[120:121], off
	s_mov_b64 exec, s[16:17]
	v_add_u32_e32 v113, 4, v113
	v_lshl_add_u64 v[120:121], v[120:121], 0, s[18:19]
	v_cmp_lt_i32_e32 vcc, s21, v113
	s_and_saveexec_b64 s[16:17], vcc
	global_load_dwordx4 v[20:23], v[120:121], off
	s_mov_b64 exec, s[16:17]
	v_add_u32_e32 v113, 4, v113
	v_lshl_add_u64 v[120:121], v[120:121], 0, s[18:19]
	v_cmp_lt_i32_e32 vcc, s21, v113
	s_and_saveexec_b64 s[16:17], vcc
	global_load_dwordx4 v[24:27], v[120:121], off
	s_mov_b64 exec, s[16:17]
	v_add_u32_e32 v113, 4, v113
	v_lshl_add_u64 v[120:121], v[120:121], 0, s[18:19]
	v_cmp_lt_i32_e32 vcc, s21, v113
	s_and_saveexec_b64 s[16:17], vcc
	global_load_dwordx4 v[28:31], v[120:121], off
	s_mov_b64 exec, s[16:17]
	v_add_u32_e32 v113, 4, v113
	v_lshl_add_u64 v[120:121], v[120:121], 0, s[18:19]
	v_cmp_lt_i32_e32 vcc, s21, v113
	s_and_saveexec_b64 s[16:17], vcc
	global_load_dwordx4 v[156:159], v[120:121], off
	s_mov_b64 exec, s[16:17]
	v_add_u32_e32 v113, 4, v113
	v_lshl_add_u64 v[120:121], v[120:121], 0, s[18:19]
	v_cmp_lt_i32_e32 vcc, s21, v113
	s_and_saveexec_b64 s[16:17], vcc
	global_load_dwordx4 v[160:163], v[120:121], off
	s_mov_b64 exec, s[16:17]
	v_add_u32_e32 v113, 4, v113
	v_lshl_add_u64 v[120:121], v[120:121], 0, s[18:19]
	v_cmp_lt_i32_e32 vcc, s21, v113
	s_and_saveexec_b64 s[16:17], vcc
	global_load_dwordx4 v[164:167], v[120:121], off
	s_mov_b64 exec, s[16:17]
	v_add_u32_e32 v113, 4, v113
	v_lshl_add_u64 v[120:121], v[120:121], 0, s[18:19]
	v_cmp_lt_i32_e32 vcc, s21, v113
	s_and_saveexec_b64 s[16:17], vcc
	global_load_dwordx4 v[168:171], v[120:121], off
	s_mov_b64 exec, s[16:17]
	v_add_u32_e32 v113, 4, v113
	v_lshl_add_u64 v[120:121], v[120:121], 0, s[18:19]
	v_cmp_lt_i32_e32 vcc, s21, v113
	s_and_saveexec_b64 s[16:17], vcc
	global_load_dwordx4 v[172:175], v[120:121], off
	s_mov_b64 exec, s[16:17]
	v_add_u32_e32 v113, 4, v113
	v_lshl_add_u64 v[120:121], v[120:121], 0, s[18:19]
	v_cmp_lt_i32_e32 vcc, s21, v113
	s_and_saveexec_b64 s[16:17], vcc
	global_load_dwordx4 v[176:179], v[120:121], off
	s_mov_b64 exec, s[16:17]
	v_add_u32_e32 v113, 4, v113
	v_lshl_add_u64 v[120:121], v[120:121], 0, s[18:19]
	v_cmp_lt_i32_e32 vcc, s21, v113
	s_and_saveexec_b64 s[16:17], vcc
	global_load_dwordx4 v[180:183], v[120:121], off
	s_mov_b64 exec, s[16:17]
	v_add_u32_e32 v113, 4, v113
	v_lshl_add_u64 v[120:121], v[120:121], 0, s[18:19]
	v_cmp_gt_u32_e32 vcc, 0x100, v207
	s_and_saveexec_b64 s[16:17], vcc
	v_cmp_lt_i32_e32 vcc, s21, v113
	s_and_b64 exec, exec, vcc
	global_load_dwordx4 v[116:119], v[120:121], off
	s_mov_b64 exec, s[16:17]
	v_add_u32_e32 v123, 0x10000, v112
	s_waitcnt vmcnt(0)
	ds_write_b128 v112, v[0:3]
	ds_write_b128 v112, v[4:7] offset:8192
	ds_write_b128 v112, v[8:11] offset:16384
	ds_write_b128 v112, v[12:15] offset:24576
	ds_write_b128 v112, v[16:19] offset:32768
	ds_write_b128 v112, v[20:23] offset:40960
	ds_write_b128 v112, v[24:27] offset:49152
	ds_write_b128 v112, v[28:31] offset:57344
	ds_write_b128 v123, v[156:159]
	ds_write_b128 v123, v[160:163] offset:8192
	ds_write_b128 v123, v[164:167] offset:16384
	ds_write_b128 v123, v[168:171] offset:24576
	ds_write_b128 v123, v[172:175] offset:32768
	ds_write_b128 v123, v[176:179] offset:40960
	ds_write_b128 v123, v[180:183] offset:49152
	v_cmp_gt_u32_e32 vcc, 0x100, v207
	s_and_saveexec_b64 s[16:17], vcc
	ds_write_b128 v123, v[116:119] offset:57344
	s_mov_b64 exec, s[16:17]

.Lat1_noresc:
	v_sub_f32_e32 v180, v200, v199
	v_sub_f32_e32 v198, v200, v201
	v_add_f32_e32 v144, v144, v180
	v_add_f32_e32 v160, v160, v198
	v_exp_f32_e32 v144, v144
	v_exp_f32_e32 v160, v160
	v_add_f32_e32 v145, v145, v180
	v_add_f32_e32 v161, v161, v198
	v_exp_f32_e32 v145, v145
	v_exp_f32_e32 v161, v161
	v_add_f32_e32 v146, v146, v180
	v_add_f32_e32 v162, v162, v198
	v_exp_f32_e32 v146, v146
	v_exp_f32_e32 v162, v162
	v_add_f32_e32 v147, v147, v180
	v_add_f32_e32 v163, v163, v198
	v_exp_f32_e32 v147, v147
	v_exp_f32_e32 v163, v163
	v_add_f32_e32 v148, v148, v180
	v_add_f32_e32 v164, v164, v198
	v_exp_f32_e32 v148, v148
	v_exp_f32_e32 v164, v164
	v_add_f32_e32 v149, v149, v180
	v_add_f32_e32 v165, v165, v198
	v_exp_f32_e32 v149, v149
	v_exp_f32_e32 v165, v165
	v_add_f32_e32 v150, v150, v180
	v_add_f32_e32 v166, v166, v198
	v_exp_f32_e32 v150, v150
	v_exp_f32_e32 v166, v166
	v_add_f32_e32 v151, v151, v180
	v_add_f32_e32 v167, v167, v198
	v_exp_f32_e32 v151, v151
	v_exp_f32_e32 v167, v167
	v_add_f32_e32 v215, v144, v145
	v_add_f32_e32 v217, v160, v161
	v_add_f32_e32 v215, v215, v146
	v_add_f32_e32 v217, v217, v162
	v_add_f32_e32 v215, v215, v147
	v_add_f32_e32 v217, v217, v163
	v_add_f32_e32 v215, v215, v148
	v_add_f32_e32 v217, v217, v164
	v_add_f32_e32 v215, v215, v149
	v_add_f32_e32 v217, v217, v165
	v_add_f32_e32 v215, v215, v150
	v_add_f32_e32 v217, v217, v166
	v_add_f32_e32 v215, v215, v151
	v_add_f32_e32 v217, v217, v167
	v_cvt_pk_bf16_f32 v144, v144, v145
	v_cvt_pk_bf16_f32 v160, v160, v161
	v_cvt_pk_bf16_f32 v145, v146, v147
	v_cvt_pk_bf16_f32 v161, v162, v163
	v_cvt_pk_bf16_f32 v146, v148, v149
	v_cvt_pk_bf16_f32 v162, v164, v165
	v_cvt_pk_bf16_f32 v147, v150, v151
	v_cvt_pk_bf16_f32 v163, v166, v167
	ds_read_b64_tr_b16 v[148:149], v216 offset:12288
	ds_read_b64_tr_b16 v[150:151], v218 offset:12288
	ds_read_b64_tr_b16 v[164:165], v220 offset:12288
	ds_read_b64_tr_b16 v[166:167], v222 offset:12288
	s_waitcnt lgkmcnt(4)
	v_mfma_f32_32x32x16_bf16 v[112:127], v[202:205], v[144:147], v[112:127]
	v_add_f32_e32 v152, v152, v180
	v_add_f32_e32 v168, v168, v198
	v_exp_f32_e32 v152, v152
	v_exp_f32_e32 v168, v168
	v_mfma_f32_32x32x16_bf16 v[96:111], v[202:205], v[160:163], v[96:111]
	v_add_f32_e32 v153, v153, v180
	v_add_f32_e32 v169, v169, v198
	v_exp_f32_e32 v153, v153
	v_exp_f32_e32 v169, v169
	ds_read_b64_tr_b16 v[202:203], v224 offset:12288
	ds_read_b64_tr_b16 v[204:205], v226 offset:12288
	v_mfma_f32_32x32x16_bf16 v[64:79], v[244:247], v[144:147], v[64:79]
	v_add_f32_e32 v154, v154, v180
	v_add_f32_e32 v170, v170, v198
	v_exp_f32_e32 v154, v154
	v_exp_f32_e32 v170, v170
	v_mfma_f32_32x32x16_bf16 v[80:95], v[244:247], v[160:163], v[80:95]
	v_add_f32_e32 v155, v155, v180
	v_add_f32_e32 v171, v171, v198
	v_exp_f32_e32 v155, v155
	v_exp_f32_e32 v171, v171
	ds_read_b64_tr_b16 v[244:245], v228 offset:12288
	ds_read_b64_tr_b16 v[246:247], v230 offset:12288
	v_mfma_f32_32x32x16_bf16 v[32:47], v[248:251], v[144:147], v[32:47]
	v_add_f32_e32 v156, v156, v180
	v_add_f32_e32 v172, v172, v198
	v_exp_f32_e32 v156, v156
	v_exp_f32_e32 v172, v172
	v_mfma_f32_32x32x16_bf16 v[48:63], v[248:251], v[160:163], v[48:63]
	v_add_f32_e32 v157, v157, v180
	v_add_f32_e32 v173, v173, v198
	v_exp_f32_e32 v157, v157
	v_exp_f32_e32 v173, v173
	v_mfma_f32_32x32x16_bf16 v[0:15], v[252:255], v[144:147], v[0:15]
	v_add_f32_e32 v158, v158, v180
	v_add_f32_e32 v174, v174, v198
	v_exp_f32_e32 v158, v158
	v_exp_f32_e32 v174, v174
	v_mfma_f32_32x32x16_bf16 v[16:31], v[252:255], v[160:163], v[16:31]
	v_add_f32_e32 v159, v159, v180
	v_add_f32_e32 v175, v175, v198
	v_exp_f32_e32 v159, v159
	v_exp_f32_e32 v175, v175
	v_cvt_pk_bf16_f32 v248, v152, v153
	v_cvt_pk_bf16_f32 v252, v168, v169
	v_cvt_pk_bf16_f32 v249, v154, v155
	v_cvt_pk_bf16_f32 v253, v170, v171
	v_cvt_pk_bf16_f32 v250, v156, v157
	v_cvt_pk_bf16_f32 v254, v172, v173
	v_cvt_pk_bf16_f32 v251, v158, v159
	v_cvt_pk_bf16_f32 v255, v174, v175
	s_nop 0
	s_waitcnt lgkmcnt(6)
	v_mfma_f32_32x32x16_bf16 v[112:127], v[148:151], v[248:251], v[112:127]
	v_add_f32_e32 v215, v215, v152
	v_add_f32_e32 v217, v217, v168
	v_mfma_f32_32x32x16_bf16 v[96:111], v[148:151], v[252:255], v[96:111]
	v_add_f32_e32 v215, v215, v153
	v_add_f32_e32 v217, v217, v169
	v_add_f32_e32 v215, v215, v154
	s_waitcnt lgkmcnt(4)
	v_mfma_f32_32x32x16_bf16 v[64:79], v[164:167], v[248:251], v[64:79]
	v_add_f32_e32 v217, v217, v170
	v_add_f32_e32 v215, v215, v155
	v_mfma_f32_32x32x16_bf16 v[80:95], v[164:167], v[252:255], v[80:95]
	v_add_f32_e32 v217, v217, v171
	v_add_f32_e32 v215, v215, v156
	v_add_f32_e32 v217, v217, v172
	s_waitcnt lgkmcnt(2)
	v_mfma_f32_32x32x16_bf16 v[32:47], v[202:205], v[248:251], v[32:47]
	v_add_f32_e32 v215, v215, v157
	v_add_f32_e32 v217, v217, v173
	v_mfma_f32_32x32x16_bf16 v[48:63], v[202:205], v[252:255], v[48:63]
	v_add_f32_e32 v215, v215, v158
	v_add_f32_e32 v217, v217, v174
	v_add_f32_e32 v215, v215, v159
	s_waitcnt lgkmcnt(0)
	v_mfma_f32_32x32x16_bf16 v[0:15], v[244:247], v[248:251], v[0:15]
	v_add_f32_e32 v217, v217, v175
	v_add_f32_e32 v197, v197, v215
	v_mfma_f32_32x32x16_bf16 v[16:31], v[244:247], v[252:255], v[16:31]
	v_add_f32_e32 v196, v196, v217
	s_cmp_gt_i32 s38, s84
	s_cbranch_scc1 .LBB0_759

.Lat2_noresc:
	v_sub_f32_e32 v180, v200, v199
	v_sub_f32_e32 v198, v200, v201
	v_add_f32_e32 v144, v144, v180
	v_add_f32_e32 v160, v160, v198
	v_exp_f32_e32 v144, v144
	v_exp_f32_e32 v160, v160
	v_add_f32_e32 v145, v145, v180
	v_add_f32_e32 v161, v161, v198
	v_exp_f32_e32 v145, v145
	v_exp_f32_e32 v161, v161
	v_add_f32_e32 v146, v146, v180
	v_add_f32_e32 v162, v162, v198
	v_exp_f32_e32 v146, v146
	v_exp_f32_e32 v162, v162
	v_add_f32_e32 v147, v147, v180
	v_add_f32_e32 v163, v163, v198
	v_exp_f32_e32 v147, v147
	v_exp_f32_e32 v163, v163
	v_add_f32_e32 v148, v148, v180
	v_add_f32_e32 v164, v164, v198
	v_exp_f32_e32 v148, v148
	v_exp_f32_e32 v164, v164
	v_add_f32_e32 v149, v149, v180
	v_add_f32_e32 v165, v165, v198
	v_exp_f32_e32 v149, v149
	v_exp_f32_e32 v165, v165
	v_add_f32_e32 v150, v150, v180
	v_add_f32_e32 v166, v166, v198
	v_exp_f32_e32 v150, v150
	v_exp_f32_e32 v166, v166
	v_add_f32_e32 v151, v151, v180
	v_add_f32_e32 v167, v167, v198
	v_exp_f32_e32 v151, v151
	v_exp_f32_e32 v167, v167
	v_add_f32_e32 v215, v144, v145
	v_add_f32_e32 v217, v160, v161
	v_add_f32_e32 v215, v215, v146
	v_add_f32_e32 v217, v217, v162
	v_add_f32_e32 v215, v215, v147
	v_add_f32_e32 v217, v217, v163
	v_add_f32_e32 v215, v215, v148
	v_add_f32_e32 v217, v217, v164
	v_add_f32_e32 v215, v215, v149
	v_add_f32_e32 v217, v217, v165
	v_add_f32_e32 v215, v215, v150
	v_add_f32_e32 v217, v217, v166
	v_add_f32_e32 v215, v215, v151
	v_add_f32_e32 v217, v217, v167
	v_cvt_pk_bf16_f32 v144, v144, v145
	v_cvt_pk_bf16_f32 v160, v160, v161
	v_cvt_pk_bf16_f32 v145, v146, v147
	v_cvt_pk_bf16_f32 v161, v162, v163
	v_cvt_pk_bf16_f32 v146, v148, v149
	v_cvt_pk_bf16_f32 v162, v164, v165
	v_cvt_pk_bf16_f32 v147, v150, v151
	v_cvt_pk_bf16_f32 v163, v166, v167
	ds_read_b64_tr_b16 v[148:149], v216 offset:4096
	ds_read_b64_tr_b16 v[150:151], v218 offset:4096
	ds_read_b64_tr_b16 v[164:165], v220 offset:4096
	ds_read_b64_tr_b16 v[166:167], v222 offset:4096
	s_waitcnt lgkmcnt(4)
	v_mfma_f32_32x32x16_bf16 v[112:127], v[202:205], v[144:147], v[112:127]
	v_add_f32_e32 v152, v152, v180
	v_add_f32_e32 v168, v168, v198
	v_exp_f32_e32 v152, v152
	v_exp_f32_e32 v168, v168
	v_mfma_f32_32x32x16_bf16 v[96:111], v[202:205], v[160:163], v[96:111]
	v_add_f32_e32 v153, v153, v180
	v_add_f32_e32 v169, v169, v198
	v_exp_f32_e32 v153, v153
	v_exp_f32_e32 v169, v169
	ds_read_b64_tr_b16 v[202:203], v224 offset:4096
	ds_read_b64_tr_b16 v[204:205], v226 offset:4096
	v_mfma_f32_32x32x16_bf16 v[64:79], v[244:247], v[144:147], v[64:79]
	v_add_f32_e32 v154, v154, v180
	v_add_f32_e32 v170, v170, v198
	v_exp_f32_e32 v154, v154
	v_exp_f32_e32 v170, v170
	v_mfma_f32_32x32x16_bf16 v[80:95], v[244:247], v[160:163], v[80:95]
	v_add_f32_e32 v155, v155, v180
	v_add_f32_e32 v171, v171, v198
	v_exp_f32_e32 v155, v155
	v_exp_f32_e32 v171, v171
	ds_read_b64_tr_b16 v[244:245], v228 offset:4096
	ds_read_b64_tr_b16 v[246:247], v230 offset:4096
	v_mfma_f32_32x32x16_bf16 v[32:47], v[248:251], v[144:147], v[32:47]
	v_add_f32_e32 v156, v156, v180
	v_add_f32_e32 v172, v172, v198
	v_exp_f32_e32 v156, v156
	v_exp_f32_e32 v172, v172
	v_mfma_f32_32x32x16_bf16 v[48:63], v[248:251], v[160:163], v[48:63]
	v_add_f32_e32 v157, v157, v180
	v_add_f32_e32 v173, v173, v198
	v_exp_f32_e32 v157, v157
	v_exp_f32_e32 v173, v173
	v_mfma_f32_32x32x16_bf16 v[0:15], v[252:255], v[144:147], v[0:15]
	v_add_f32_e32 v158, v158, v180
	v_add_f32_e32 v174, v174, v198
	v_exp_f32_e32 v158, v158
	v_exp_f32_e32 v174, v174
	v_mfma_f32_32x32x16_bf16 v[16:31], v[252:255], v[160:163], v[16:31]
	v_add_f32_e32 v159, v159, v180
	v_add_f32_e32 v175, v175, v198
	v_exp_f32_e32 v159, v159
	v_exp_f32_e32 v175, v175
	v_cvt_pk_bf16_f32 v248, v152, v153
	v_cvt_pk_bf16_f32 v252, v168, v169
	v_cvt_pk_bf16_f32 v249, v154, v155
	v_cvt_pk_bf16_f32 v253, v170, v171
	v_cvt_pk_bf16_f32 v250, v156, v157
	v_cvt_pk_bf16_f32 v254, v172, v173
	v_cvt_pk_bf16_f32 v251, v158, v159
	v_cvt_pk_bf16_f32 v255, v174, v175
	s_nop 0
	s_waitcnt lgkmcnt(6)
	v_mfma_f32_32x32x16_bf16 v[112:127], v[148:151], v[248:251], v[112:127]
	v_add_f32_e32 v215, v215, v152
	v_add_f32_e32 v217, v217, v168
	v_mfma_f32_32x32x16_bf16 v[96:111], v[148:151], v[252:255], v[96:111]
	v_add_f32_e32 v215, v215, v153
	v_add_f32_e32 v217, v217, v169
	v_add_f32_e32 v215, v215, v154
	s_waitcnt lgkmcnt(4)
	v_mfma_f32_32x32x16_bf16 v[64:79], v[164:167], v[248:251], v[64:79]
	v_add_f32_e32 v217, v217, v170
	v_add_f32_e32 v215, v215, v155
	v_mfma_f32_32x32x16_bf16 v[80:95], v[164:167], v[252:255], v[80:95]
	v_add_f32_e32 v217, v217, v171
	v_add_f32_e32 v215, v215, v156
	v_add_f32_e32 v217, v217, v172
	s_waitcnt lgkmcnt(2)
	v_mfma_f32_32x32x16_bf16 v[32:47], v[202:205], v[248:251], v[32:47]
	v_add_f32_e32 v215, v215, v157
	v_add_f32_e32 v217, v217, v173
	v_mfma_f32_32x32x16_bf16 v[48:63], v[202:205], v[252:255], v[48:63]
	v_add_f32_e32 v215, v215, v158
	v_add_f32_e32 v217, v217, v174
	v_add_f32_e32 v215, v215, v159
	s_waitcnt lgkmcnt(0)
	v_mfma_f32_32x32x16_bf16 v[0:15], v[244:247], v[248:251], v[0:15]
	v_add_f32_e32 v217, v217, v175
	v_add_f32_e32 v197, v197, v215
	v_mfma_f32_32x32x16_bf16 v[16:31], v[244:247], v[252:255], v[16:31]
	v_add_f32_e32 v196, v196, v217
	s_add_i32 s78, s41, 1
	s_cmp_ge_u32 s78, s85
	s_cbranch_scc1 .LBB0_778

.Lat3_noresc:
	v_sub_f32_e32 v180, v200, v199
	v_sub_f32_e32 v198, v200, v201
	v_add_f32_e32 v144, v144, v180
	v_add_f32_e32 v160, v160, v198
	v_exp_f32_e32 v144, v144
	v_exp_f32_e32 v160, v160
	v_add_f32_e32 v145, v145, v180
	v_add_f32_e32 v161, v161, v198
	v_exp_f32_e32 v145, v145
	v_exp_f32_e32 v161, v161
	v_add_f32_e32 v146, v146, v180
	v_add_f32_e32 v162, v162, v198
	v_exp_f32_e32 v146, v146
	v_exp_f32_e32 v162, v162
	v_add_f32_e32 v147, v147, v180
	v_add_f32_e32 v163, v163, v198
	v_exp_f32_e32 v147, v147
	v_exp_f32_e32 v163, v163
	v_add_f32_e32 v148, v148, v180
	v_add_f32_e32 v164, v164, v198
	v_exp_f32_e32 v148, v148
	v_exp_f32_e32 v164, v164
	v_add_f32_e32 v149, v149, v180
	v_add_f32_e32 v165, v165, v198
	v_exp_f32_e32 v149, v149
	v_exp_f32_e32 v165, v165
	v_add_f32_e32 v150, v150, v180
	v_add_f32_e32 v166, v166, v198
	v_exp_f32_e32 v150, v150
	v_exp_f32_e32 v166, v166
	v_add_f32_e32 v151, v151, v180
	v_add_f32_e32 v167, v167, v198
	v_exp_f32_e32 v151, v151
	v_exp_f32_e32 v167, v167
	v_add_f32_e32 v215, v144, v145
	v_add_f32_e32 v217, v160, v161
	v_add_f32_e32 v215, v215, v146
	v_add_f32_e32 v217, v217, v162
	v_add_f32_e32 v215, v215, v147
	v_add_f32_e32 v217, v217, v163
	v_add_f32_e32 v215, v215, v148
	v_add_f32_e32 v217, v217, v164
	v_add_f32_e32 v215, v215, v149
	v_add_f32_e32 v217, v217, v165
	v_add_f32_e32 v215, v215, v150
	v_add_f32_e32 v217, v217, v166
	v_add_f32_e32 v215, v215, v151
	v_add_f32_e32 v217, v217, v167
	v_cvt_pk_bf16_f32 v144, v144, v145
	v_cvt_pk_bf16_f32 v160, v160, v161
	v_cvt_pk_bf16_f32 v145, v146, v147
	v_cvt_pk_bf16_f32 v161, v162, v163
	v_cvt_pk_bf16_f32 v146, v148, v149
	v_cvt_pk_bf16_f32 v162, v164, v165
	v_cvt_pk_bf16_f32 v147, v150, v151
	v_cvt_pk_bf16_f32 v163, v166, v167
	ds_read_b64_tr_b16 v[148:149], v216 offset:28672
	ds_read_b64_tr_b16 v[150:151], v218 offset:28672
	ds_read_b64_tr_b16 v[164:165], v220 offset:28672
	ds_read_b64_tr_b16 v[166:167], v222 offset:28672
	s_waitcnt lgkmcnt(4)
	v_mfma_f32_32x32x16_bf16 v[112:127], v[202:205], v[144:147], v[112:127]
	v_add_f32_e32 v152, v152, v180
	v_add_f32_e32 v168, v168, v198
	v_exp_f32_e32 v152, v152
	v_exp_f32_e32 v168, v168
	v_mfma_f32_32x32x16_bf16 v[96:111], v[202:205], v[160:163], v[96:111]
	v_add_f32_e32 v153, v153, v180
	v_add_f32_e32 v169, v169, v198
	v_exp_f32_e32 v153, v153
	v_exp_f32_e32 v169, v169
	ds_read_b64_tr_b16 v[202:203], v224 offset:28672
	ds_read_b64_tr_b16 v[204:205], v226 offset:28672
	v_mfma_f32_32x32x16_bf16 v[64:79], v[244:247], v[144:147], v[64:79]
	v_add_f32_e32 v154, v154, v180
	v_add_f32_e32 v170, v170, v198
	v_exp_f32_e32 v154, v154
	v_exp_f32_e32 v170, v170
	v_mfma_f32_32x32x16_bf16 v[80:95], v[244:247], v[160:163], v[80:95]
	v_add_f32_e32 v155, v155, v180
	v_add_f32_e32 v171, v171, v198
	v_exp_f32_e32 v155, v155
	v_exp_f32_e32 v171, v171
	ds_read_b64_tr_b16 v[244:245], v228 offset:28672
	ds_read_b64_tr_b16 v[246:247], v230 offset:28672
	v_mfma_f32_32x32x16_bf16 v[32:47], v[248:251], v[144:147], v[32:47]
	v_add_f32_e32 v156, v156, v180
	v_add_f32_e32 v172, v172, v198
	v_exp_f32_e32 v156, v156
	v_exp_f32_e32 v172, v172
	v_mfma_f32_32x32x16_bf16 v[48:63], v[248:251], v[160:163], v[48:63]
	v_add_f32_e32 v157, v157, v180
	v_add_f32_e32 v173, v173, v198
	v_exp_f32_e32 v157, v157
	v_exp_f32_e32 v173, v173
	v_mfma_f32_32x32x16_bf16 v[0:15], v[252:255], v[144:147], v[0:15]
	v_add_f32_e32 v158, v158, v180
	v_add_f32_e32 v174, v174, v198
	v_exp_f32_e32 v158, v158
	v_exp_f32_e32 v174, v174
	v_mfma_f32_32x32x16_bf16 v[16:31], v[252:255], v[160:163], v[16:31]
	v_add_f32_e32 v159, v159, v180
	v_add_f32_e32 v175, v175, v198
	v_exp_f32_e32 v159, v159
	v_exp_f32_e32 v175, v175
	v_cvt_pk_bf16_f32 v248, v152, v153
	v_cvt_pk_bf16_f32 v252, v168, v169
	v_cvt_pk_bf16_f32 v249, v154, v155
	v_cvt_pk_bf16_f32 v253, v170, v171
	v_cvt_pk_bf16_f32 v250, v156, v157
	v_cvt_pk_bf16_f32 v254, v172, v173
	v_cvt_pk_bf16_f32 v251, v158, v159
	v_cvt_pk_bf16_f32 v255, v174, v175
	s_nop 0
	s_waitcnt lgkmcnt(6)
	v_mfma_f32_32x32x16_bf16 v[112:127], v[148:151], v[248:251], v[112:127]
	v_add_f32_e32 v215, v215, v152
	v_add_f32_e32 v217, v217, v168
	v_mfma_f32_32x32x16_bf16 v[96:111], v[148:151], v[252:255], v[96:111]
	v_add_f32_e32 v215, v215, v153
	v_add_f32_e32 v217, v217, v169
	v_add_f32_e32 v215, v215, v154
	s_waitcnt lgkmcnt(4)
	v_mfma_f32_32x32x16_bf16 v[64:79], v[164:167], v[248:251], v[64:79]
	v_add_f32_e32 v217, v217, v170
	v_add_f32_e32 v215, v215, v155
	v_mfma_f32_32x32x16_bf16 v[80:95], v[164:167], v[252:255], v[80:95]
	v_add_f32_e32 v217, v217, v171
	v_add_f32_e32 v215, v215, v156
	v_add_f32_e32 v217, v217, v172
	s_waitcnt lgkmcnt(2)
	v_mfma_f32_32x32x16_bf16 v[32:47], v[202:205], v[248:251], v[32:47]
	v_add_f32_e32 v215, v215, v157
	v_add_f32_e32 v217, v217, v173
	v_mfma_f32_32x32x16_bf16 v[48:63], v[202:205], v[252:255], v[48:63]
	v_add_f32_e32 v215, v215, v158
	v_add_f32_e32 v217, v217, v174
	v_add_f32_e32 v215, v215, v159
	s_waitcnt lgkmcnt(0)
	v_mfma_f32_32x32x16_bf16 v[0:15], v[244:247], v[248:251], v[0:15]
	v_add_f32_e32 v217, v217, v175
	v_add_f32_e32 v197, v197, v215
	v_mfma_f32_32x32x16_bf16 v[16:31], v[244:247], v[252:255], v[16:31]
	v_add_f32_e32 v196, v196, v217
	s_cmp_gt_i32 s78, s84
	s_cbranch_scc1 .LBB0_778

.Lat4_noresc:
	v_sub_f32_e32 v180, v200, v199
	v_sub_f32_e32 v198, v200, v201
	v_add_f32_e32 v144, v144, v180
	v_add_f32_e32 v160, v160, v198
	v_exp_f32_e32 v144, v144
	v_exp_f32_e32 v160, v160
	v_add_f32_e32 v145, v145, v180
	v_add_f32_e32 v161, v161, v198
	v_exp_f32_e32 v145, v145
	v_exp_f32_e32 v161, v161
	v_add_f32_e32 v146, v146, v180
	v_add_f32_e32 v162, v162, v198
	v_exp_f32_e32 v146, v146
	v_exp_f32_e32 v162, v162
	v_add_f32_e32 v147, v147, v180
	v_add_f32_e32 v163, v163, v198
	v_exp_f32_e32 v147, v147
	v_exp_f32_e32 v163, v163
	v_add_f32_e32 v148, v148, v180
	v_add_f32_e32 v164, v164, v198
	v_exp_f32_e32 v148, v148
	v_exp_f32_e32 v164, v164
	v_add_f32_e32 v149, v149, v180
	v_add_f32_e32 v165, v165, v198
	v_exp_f32_e32 v149, v149
	v_exp_f32_e32 v165, v165
	v_add_f32_e32 v150, v150, v180
	v_add_f32_e32 v166, v166, v198
	v_exp_f32_e32 v150, v150
	v_exp_f32_e32 v166, v166
	v_add_f32_e32 v151, v151, v180
	v_add_f32_e32 v167, v167, v198
	v_exp_f32_e32 v151, v151
	v_exp_f32_e32 v167, v167
	v_add_f32_e32 v215, v144, v145
	v_add_f32_e32 v217, v160, v161
	v_add_f32_e32 v215, v215, v146
	v_add_f32_e32 v217, v217, v162
	v_add_f32_e32 v215, v215, v147
	v_add_f32_e32 v217, v217, v163
	v_add_f32_e32 v215, v215, v148
	v_add_f32_e32 v217, v217, v164
	v_add_f32_e32 v215, v215, v149
	v_add_f32_e32 v217, v217, v165
	v_add_f32_e32 v215, v215, v150
	v_add_f32_e32 v217, v217, v166
	v_add_f32_e32 v215, v215, v151
	v_add_f32_e32 v217, v217, v167
	v_cvt_pk_bf16_f32 v144, v144, v145
	v_cvt_pk_bf16_f32 v160, v160, v161
	v_cvt_pk_bf16_f32 v145, v146, v147
	v_cvt_pk_bf16_f32 v161, v162, v163
	v_cvt_pk_bf16_f32 v146, v148, v149
	v_cvt_pk_bf16_f32 v162, v164, v165
	v_cvt_pk_bf16_f32 v147, v150, v151
	v_cvt_pk_bf16_f32 v163, v166, v167
	ds_read_b64_tr_b16 v[148:149], v216 offset:20480
	ds_read_b64_tr_b16 v[150:151], v218 offset:20480
	ds_read_b64_tr_b16 v[164:165], v220 offset:20480
	ds_read_b64_tr_b16 v[166:167], v222 offset:20480
	s_waitcnt lgkmcnt(4)
	v_mfma_f32_32x32x16_bf16 v[112:127], v[202:205], v[144:147], v[112:127]
	v_add_f32_e32 v152, v152, v180
	v_add_f32_e32 v168, v168, v198
	v_exp_f32_e32 v152, v152
	v_exp_f32_e32 v168, v168
	v_mfma_f32_32x32x16_bf16 v[96:111], v[202:205], v[160:163], v[96:111]
	v_add_f32_e32 v153, v153, v180
	v_add_f32_e32 v169, v169, v198
	v_exp_f32_e32 v153, v153
	v_exp_f32_e32 v169, v169
	ds_read_b64_tr_b16 v[202:203], v224 offset:20480
	ds_read_b64_tr_b16 v[204:205], v226 offset:20480
	v_mfma_f32_32x32x16_bf16 v[64:79], v[244:247], v[144:147], v[64:79]
	v_add_f32_e32 v154, v154, v180
	v_add_f32_e32 v170, v170, v198
	v_exp_f32_e32 v154, v154
	v_exp_f32_e32 v170, v170
	v_mfma_f32_32x32x16_bf16 v[80:95], v[244:247], v[160:163], v[80:95]
	v_add_f32_e32 v155, v155, v180
	v_add_f32_e32 v171, v171, v198
	v_exp_f32_e32 v155, v155
	v_exp_f32_e32 v171, v171
	ds_read_b64_tr_b16 v[244:245], v228 offset:20480
	ds_read_b64_tr_b16 v[246:247], v230 offset:20480
	v_mfma_f32_32x32x16_bf16 v[32:47], v[248:251], v[144:147], v[32:47]
	v_add_f32_e32 v156, v156, v180
	v_add_f32_e32 v172, v172, v198
	v_exp_f32_e32 v156, v156
	v_exp_f32_e32 v172, v172
	v_mfma_f32_32x32x16_bf16 v[48:63], v[248:251], v[160:163], v[48:63]
	v_add_f32_e32 v157, v157, v180
	v_add_f32_e32 v173, v173, v198
	v_exp_f32_e32 v157, v157
	v_exp_f32_e32 v173, v173
	v_mfma_f32_32x32x16_bf16 v[0:15], v[252:255], v[144:147], v[0:15]
	v_add_f32_e32 v158, v158, v180
	v_add_f32_e32 v174, v174, v198
	v_exp_f32_e32 v158, v158
	v_exp_f32_e32 v174, v174
	v_mfma_f32_32x32x16_bf16 v[16:31], v[252:255], v[160:163], v[16:31]
	v_add_f32_e32 v159, v159, v180
	v_add_f32_e32 v175, v175, v198
	v_exp_f32_e32 v159, v159
	v_exp_f32_e32 v175, v175
	v_cvt_pk_bf16_f32 v248, v152, v153
	v_cvt_pk_bf16_f32 v252, v168, v169
	v_cvt_pk_bf16_f32 v249, v154, v155
	v_cvt_pk_bf16_f32 v253, v170, v171
	v_cvt_pk_bf16_f32 v250, v156, v157
	v_cvt_pk_bf16_f32 v254, v172, v173
	v_cvt_pk_bf16_f32 v251, v158, v159
	v_cvt_pk_bf16_f32 v255, v174, v175
	s_nop 0
	s_waitcnt lgkmcnt(6)
	v_mfma_f32_32x32x16_bf16 v[112:127], v[148:151], v[248:251], v[112:127]
	v_add_f32_e32 v215, v215, v152
	v_add_f32_e32 v217, v217, v168
	v_mfma_f32_32x32x16_bf16 v[96:111], v[148:151], v[252:255], v[96:111]
	v_add_f32_e32 v215, v215, v153
	v_add_f32_e32 v217, v217, v169
	v_add_f32_e32 v215, v215, v154
	s_waitcnt lgkmcnt(4)
	v_mfma_f32_32x32x16_bf16 v[64:79], v[164:167], v[248:251], v[64:79]
	v_add_f32_e32 v217, v217, v170
	v_add_f32_e32 v215, v215, v155
	v_mfma_f32_32x32x16_bf16 v[80:95], v[164:167], v[252:255], v[80:95]
	v_add_f32_e32 v217, v217, v171
	v_add_f32_e32 v215, v215, v156
	v_add_f32_e32 v217, v217, v172
	s_waitcnt lgkmcnt(2)
	v_mfma_f32_32x32x16_bf16 v[32:47], v[202:205], v[248:251], v[32:47]
	v_add_f32_e32 v215, v215, v157
	v_add_f32_e32 v217, v217, v173
	v_mfma_f32_32x32x16_bf16 v[48:63], v[202:205], v[252:255], v[48:63]
	v_add_f32_e32 v215, v215, v158
	v_add_f32_e32 v217, v217, v174
	v_add_f32_e32 v215, v215, v159
	s_waitcnt lgkmcnt(0)
	v_mfma_f32_32x32x16_bf16 v[0:15], v[244:247], v[248:251], v[0:15]
	v_add_f32_e32 v217, v217, v175
	v_add_f32_e32 v197, v197, v215
	v_mfma_f32_32x32x16_bf16 v[16:31], v[244:247], v[252:255], v[16:31]
	v_add_f32_e32 v196, v196, v217
	s_add_i32 s0, s41, 2
	s_cmp_ge_u32 s0, s85
	s_cbranch_scc1 .LBB0_753
	s_branch .LBB0_779

.Lat5_noresc:
	v_sub_f32_e32 v180, v200, v199
	v_sub_f32_e32 v198, v200, v201
	v_add_f32_e32 v144, v144, v180
	v_add_f32_e32 v160, v160, v198
	v_exp_f32_e32 v144, v144
	v_exp_f32_e32 v160, v160
	v_add_f32_e32 v145, v145, v180
	v_add_f32_e32 v161, v161, v198
	v_exp_f32_e32 v145, v145
	v_exp_f32_e32 v161, v161
	v_add_f32_e32 v146, v146, v180
	v_add_f32_e32 v162, v162, v198
	v_exp_f32_e32 v146, v146
	v_exp_f32_e32 v162, v162
	v_add_f32_e32 v147, v147, v180
	v_add_f32_e32 v163, v163, v198
	v_exp_f32_e32 v147, v147
	v_exp_f32_e32 v163, v163
	v_add_f32_e32 v148, v148, v180
	v_add_f32_e32 v164, v164, v198
	v_exp_f32_e32 v148, v148
	v_exp_f32_e32 v164, v164
	v_add_f32_e32 v149, v149, v180
	v_add_f32_e32 v165, v165, v198
	v_exp_f32_e32 v149, v149
	v_exp_f32_e32 v165, v165
	v_add_f32_e32 v150, v150, v180
	v_add_f32_e32 v166, v166, v198
	v_exp_f32_e32 v150, v150
	v_exp_f32_e32 v166, v166
	v_add_f32_e32 v151, v151, v180
	v_add_f32_e32 v167, v167, v198
	v_exp_f32_e32 v151, v151
	v_exp_f32_e32 v167, v167
	v_add_f32_e32 v215, v144, v145
	v_add_f32_e32 v217, v160, v161
	v_add_f32_e32 v215, v215, v146
	v_add_f32_e32 v217, v217, v162
	v_add_f32_e32 v215, v215, v147
	v_add_f32_e32 v217, v217, v163
	v_add_f32_e32 v215, v215, v148
	v_add_f32_e32 v217, v217, v164
	v_add_f32_e32 v215, v215, v149
	v_add_f32_e32 v217, v217, v165
	v_add_f32_e32 v215, v215, v150
	v_add_f32_e32 v217, v217, v166
	v_add_f32_e32 v215, v215, v151
	v_add_f32_e32 v217, v217, v167
	v_cvt_pk_bf16_f32 v144, v144, v145
	v_cvt_pk_bf16_f32 v160, v160, v161
	v_cvt_pk_bf16_f32 v145, v146, v147
	v_cvt_pk_bf16_f32 v161, v162, v163
	v_cvt_pk_bf16_f32 v146, v148, v149
	v_cvt_pk_bf16_f32 v162, v164, v165
	v_cvt_pk_bf16_f32 v147, v150, v151
	v_cvt_pk_bf16_f32 v163, v166, v167
	ds_read_b64_tr_b16 v[148:149], v216 offset:45056
	ds_read_b64_tr_b16 v[150:151], v218 offset:45056
	ds_read_b64_tr_b16 v[164:165], v220 offset:45056
	ds_read_b64_tr_b16 v[166:167], v222 offset:45056
	s_waitcnt lgkmcnt(4)
	v_mfma_f32_32x32x16_bf16 v[112:127], v[202:205], v[144:147], v[112:127]
	v_add_f32_e32 v152, v152, v180
	v_add_f32_e32 v168, v168, v198
	v_exp_f32_e32 v152, v152
	v_exp_f32_e32 v168, v168
	v_mfma_f32_32x32x16_bf16 v[96:111], v[202:205], v[160:163], v[96:111]
	v_add_f32_e32 v153, v153, v180
	v_add_f32_e32 v169, v169, v198
	v_exp_f32_e32 v153, v153
	v_exp_f32_e32 v169, v169
	ds_read_b64_tr_b16 v[202:203], v224 offset:45056
	ds_read_b64_tr_b16 v[204:205], v226 offset:45056
	v_mfma_f32_32x32x16_bf16 v[64:79], v[244:247], v[144:147], v[64:79]
	v_add_f32_e32 v154, v154, v180
	v_add_f32_e32 v170, v170, v198
	v_exp_f32_e32 v154, v154
	v_exp_f32_e32 v170, v170
	v_mfma_f32_32x32x16_bf16 v[80:95], v[244:247], v[160:163], v[80:95]
	v_add_f32_e32 v155, v155, v180
	v_add_f32_e32 v171, v171, v198
	v_exp_f32_e32 v155, v155
	v_exp_f32_e32 v171, v171
	ds_read_b64_tr_b16 v[244:245], v228 offset:45056
	ds_read_b64_tr_b16 v[246:247], v230 offset:45056
	v_mfma_f32_32x32x16_bf16 v[32:47], v[248:251], v[144:147], v[32:47]
	v_add_f32_e32 v156, v156, v180
	v_add_f32_e32 v172, v172, v198
	v_exp_f32_e32 v156, v156
	v_exp_f32_e32 v172, v172
	v_mfma_f32_32x32x16_bf16 v[48:63], v[248:251], v[160:163], v[48:63]
	v_add_f32_e32 v157, v157, v180
	v_add_f32_e32 v173, v173, v198
	v_exp_f32_e32 v157, v157
	v_exp_f32_e32 v173, v173
	v_mfma_f32_32x32x16_bf16 v[0:15], v[252:255], v[144:147], v[0:15]
	v_add_f32_e32 v158, v158, v180
	v_add_f32_e32 v174, v174, v198
	v_exp_f32_e32 v158, v158
	v_exp_f32_e32 v174, v174
	v_mfma_f32_32x32x16_bf16 v[16:31], v[252:255], v[160:163], v[16:31]
	v_add_f32_e32 v159, v159, v180
	v_add_f32_e32 v175, v175, v198
	v_exp_f32_e32 v159, v159
	v_exp_f32_e32 v175, v175
	v_cvt_pk_bf16_f32 v248, v152, v153
	v_cvt_pk_bf16_f32 v252, v168, v169
	v_cvt_pk_bf16_f32 v249, v154, v155
	v_cvt_pk_bf16_f32 v253, v170, v171
	v_cvt_pk_bf16_f32 v250, v156, v157
	v_cvt_pk_bf16_f32 v254, v172, v173
	v_cvt_pk_bf16_f32 v251, v158, v159
	v_cvt_pk_bf16_f32 v255, v174, v175
	s_nop 0
	s_waitcnt lgkmcnt(6)
	v_mfma_f32_32x32x16_bf16 v[112:127], v[148:151], v[248:251], v[112:127]
	v_add_f32_e32 v215, v215, v152
	v_add_f32_e32 v217, v217, v168
	v_mfma_f32_32x32x16_bf16 v[96:111], v[148:151], v[252:255], v[96:111]
	v_add_f32_e32 v215, v215, v153
	v_add_f32_e32 v217, v217, v169
	v_add_f32_e32 v215, v215, v154
	s_waitcnt lgkmcnt(4)
	v_mfma_f32_32x32x16_bf16 v[64:79], v[164:167], v[248:251], v[64:79]
	v_add_f32_e32 v217, v217, v170
	v_add_f32_e32 v215, v215, v155
	v_mfma_f32_32x32x16_bf16 v[80:95], v[164:167], v[252:255], v[80:95]
	v_add_f32_e32 v217, v217, v171
	v_add_f32_e32 v215, v215, v156
	v_add_f32_e32 v217, v217, v172
	s_waitcnt lgkmcnt(2)
	v_mfma_f32_32x32x16_bf16 v[32:47], v[202:205], v[248:251], v[32:47]
	v_add_f32_e32 v215, v215, v157
	v_add_f32_e32 v217, v217, v173
	v_mfma_f32_32x32x16_bf16 v[48:63], v[202:205], v[252:255], v[48:63]
	v_add_f32_e32 v215, v215, v158
	v_add_f32_e32 v217, v217, v174
	v_add_f32_e32 v215, v215, v159
	s_waitcnt lgkmcnt(0)
	v_mfma_f32_32x32x16_bf16 v[0:15], v[244:247], v[248:251], v[0:15]
	v_add_f32_e32 v217, v217, v175
	v_add_f32_e32 v197, v197, v215
	v_mfma_f32_32x32x16_bf16 v[16:31], v[244:247], v[252:255], v[16:31]
	v_add_f32_e32 v196, v196, v217
	s_cmp_gt_i32 s78, s84
	s_cbranch_scc1 .LBB0_753

.Lat6_noresc:
	v_sub_f32_e32 v180, v200, v199
	v_sub_f32_e32 v198, v200, v201
	v_add_f32_e32 v144, v144, v180
	v_add_f32_e32 v160, v160, v198
	v_exp_f32_e32 v144, v144
	v_exp_f32_e32 v160, v160
	v_add_f32_e32 v145, v145, v180
	v_add_f32_e32 v161, v161, v198
	v_exp_f32_e32 v145, v145
	v_exp_f32_e32 v161, v161
	v_add_f32_e32 v146, v146, v180
	v_add_f32_e32 v162, v162, v198
	v_exp_f32_e32 v146, v146
	v_exp_f32_e32 v162, v162
	v_add_f32_e32 v147, v147, v180
	v_add_f32_e32 v163, v163, v198
	v_exp_f32_e32 v147, v147
	v_exp_f32_e32 v163, v163
	v_add_f32_e32 v148, v148, v180
	v_add_f32_e32 v164, v164, v198
	v_exp_f32_e32 v148, v148
	v_exp_f32_e32 v164, v164
	v_add_f32_e32 v149, v149, v180
	v_add_f32_e32 v165, v165, v198
	v_exp_f32_e32 v149, v149
	v_exp_f32_e32 v165, v165
	v_add_f32_e32 v150, v150, v180
	v_add_f32_e32 v166, v166, v198
	v_exp_f32_e32 v150, v150
	v_exp_f32_e32 v166, v166
	v_add_f32_e32 v151, v151, v180
	v_add_f32_e32 v167, v167, v198
	v_exp_f32_e32 v151, v151
	v_exp_f32_e32 v167, v167
	v_add_f32_e32 v215, v144, v145
	v_add_f32_e32 v217, v160, v161
	v_add_f32_e32 v215, v215, v146
	v_add_f32_e32 v217, v217, v162
	v_add_f32_e32 v215, v215, v147
	v_add_f32_e32 v217, v217, v163
	v_add_f32_e32 v215, v215, v148
	v_add_f32_e32 v217, v217, v164
	v_add_f32_e32 v215, v215, v149
	v_add_f32_e32 v217, v217, v165
	v_add_f32_e32 v215, v215, v150
	v_add_f32_e32 v217, v217, v166
	v_add_f32_e32 v215, v215, v151
	v_add_f32_e32 v217, v217, v167
	v_cvt_pk_bf16_f32 v144, v144, v145
	v_cvt_pk_bf16_f32 v160, v160, v161
	v_cvt_pk_bf16_f32 v145, v146, v147
	v_cvt_pk_bf16_f32 v161, v162, v163
	v_cvt_pk_bf16_f32 v146, v148, v149
	v_cvt_pk_bf16_f32 v162, v164, v165
	v_cvt_pk_bf16_f32 v147, v150, v151
	v_cvt_pk_bf16_f32 v163, v166, v167
	ds_read_b64_tr_b16 v[148:149], v216 offset:36864
	ds_read_b64_tr_b16 v[150:151], v218 offset:36864
	ds_read_b64_tr_b16 v[164:165], v220 offset:36864
	ds_read_b64_tr_b16 v[166:167], v222 offset:36864
	s_waitcnt lgkmcnt(4)
	v_mfma_f32_32x32x16_bf16 v[112:127], v[202:205], v[144:147], v[112:127]
	v_add_f32_e32 v152, v152, v180
	v_add_f32_e32 v168, v168, v198
	v_exp_f32_e32 v152, v152
	v_exp_f32_e32 v168, v168
	v_mfma_f32_32x32x16_bf16 v[96:111], v[202:205], v[160:163], v[96:111]
	v_add_f32_e32 v153, v153, v180
	v_add_f32_e32 v169, v169, v198
	v_exp_f32_e32 v153, v153
	v_exp_f32_e32 v169, v169
	ds_read_b64_tr_b16 v[202:203], v224 offset:36864
	ds_read_b64_tr_b16 v[204:205], v226 offset:36864
	v_mfma_f32_32x32x16_bf16 v[64:79], v[244:247], v[144:147], v[64:79]
	v_add_f32_e32 v154, v154, v180
	v_add_f32_e32 v170, v170, v198
	v_exp_f32_e32 v154, v154
	v_exp_f32_e32 v170, v170
	v_mfma_f32_32x32x16_bf16 v[80:95], v[244:247], v[160:163], v[80:95]
	v_add_f32_e32 v155, v155, v180
	v_add_f32_e32 v171, v171, v198
	v_exp_f32_e32 v155, v155
	v_exp_f32_e32 v171, v171
	ds_read_b64_tr_b16 v[244:245], v228 offset:36864
	ds_read_b64_tr_b16 v[246:247], v230 offset:36864
	v_mfma_f32_32x32x16_bf16 v[32:47], v[248:251], v[144:147], v[32:47]
	v_add_f32_e32 v156, v156, v180
	v_add_f32_e32 v172, v172, v198
	v_exp_f32_e32 v156, v156
	v_exp_f32_e32 v172, v172
	v_mfma_f32_32x32x16_bf16 v[48:63], v[248:251], v[160:163], v[48:63]
	v_add_f32_e32 v157, v157, v180
	v_add_f32_e32 v173, v173, v198
	v_exp_f32_e32 v157, v157
	v_exp_f32_e32 v173, v173
	v_mfma_f32_32x32x16_bf16 v[0:15], v[252:255], v[144:147], v[0:15]
	v_add_f32_e32 v158, v158, v180
	v_add_f32_e32 v174, v174, v198
	v_exp_f32_e32 v158, v158
	v_exp_f32_e32 v174, v174
	v_mfma_f32_32x32x16_bf16 v[16:31], v[252:255], v[160:163], v[16:31]
	v_add_f32_e32 v159, v159, v180
	v_add_f32_e32 v175, v175, v198
	v_exp_f32_e32 v159, v159
	v_exp_f32_e32 v175, v175
	v_cvt_pk_bf16_f32 v248, v152, v153
	v_cvt_pk_bf16_f32 v252, v168, v169
	v_cvt_pk_bf16_f32 v249, v154, v155
	v_cvt_pk_bf16_f32 v253, v170, v171
	v_cvt_pk_bf16_f32 v250, v156, v157
	v_cvt_pk_bf16_f32 v254, v172, v173
	v_cvt_pk_bf16_f32 v251, v158, v159
	v_cvt_pk_bf16_f32 v255, v174, v175
	s_nop 0
	s_waitcnt lgkmcnt(6)
	v_mfma_f32_32x32x16_bf16 v[112:127], v[148:151], v[248:251], v[112:127]
	v_add_f32_e32 v215, v215, v152
	v_add_f32_e32 v217, v217, v168
	v_mfma_f32_32x32x16_bf16 v[96:111], v[148:151], v[252:255], v[96:111]
	v_add_f32_e32 v215, v215, v153
	v_add_f32_e32 v217, v217, v169
	v_add_f32_e32 v215, v215, v154
	s_waitcnt lgkmcnt(4)
	v_mfma_f32_32x32x16_bf16 v[64:79], v[164:167], v[248:251], v[64:79]
	v_add_f32_e32 v217, v217, v170
	v_add_f32_e32 v215, v215, v155
	v_mfma_f32_32x32x16_bf16 v[80:95], v[164:167], v[252:255], v[80:95]
	v_add_f32_e32 v217, v217, v171
	v_add_f32_e32 v215, v215, v156
	v_add_f32_e32 v217, v217, v172
	s_waitcnt lgkmcnt(2)
	v_mfma_f32_32x32x16_bf16 v[32:47], v[202:205], v[248:251], v[32:47]
	v_add_f32_e32 v215, v215, v157
	v_add_f32_e32 v217, v217, v173
	v_mfma_f32_32x32x16_bf16 v[48:63], v[202:205], v[252:255], v[48:63]
	v_add_f32_e32 v215, v215, v158
	v_add_f32_e32 v217, v217, v174
	v_add_f32_e32 v215, v215, v159
	s_waitcnt lgkmcnt(0)
	v_mfma_f32_32x32x16_bf16 v[0:15], v[244:247], v[248:251], v[0:15]
	v_add_f32_e32 v217, v217, v175
	v_add_f32_e32 v197, v197, v215
	v_mfma_f32_32x32x16_bf16 v[16:31], v[244:247], v[252:255], v[16:31]
	v_add_f32_e32 v196, v196, v217
	s_branch .LBB0_753
